# prologue de-serialisation: second DMA batch of all 9 GEMM prologues issued before the first wait (vmcnt 2->8), on top of boff+ntK
# baseline (speedup 1.0000x reference)
; #define PG8_STAGE(bufoff, gbase, voff) do { _Pragma("unroll") for (int _i = 0; _i < 2; ++_i) \
;         __builtin_amdgcn_global_load_lds((const unsigned*)((const char*)(gbase) + (voff)[_i]), (PG8_LAS unsigned*)(lds + (bufoff) + ldsw + _i * 8192), 16, 0, 0); } while (0)
; #define PG8_WAIT_V(n) asm volatile("s_waitcnt vmcnt(" #n ")" ::: "memory")
; #define PG8_BAR __builtin_amdgcn_s_barrier()
; template <class Epi, class Sched, bool ALIGN_EPI = false, bool SP2 = false>
; __device__ __forceinline__ void gemm_phase(PG8_LAS unsigned char* lds, const Gemm g, const Sched& S, const Epi& E) {
;     ...
;     const char* cA = (const char*)g.A + (size_t)cur.pm * tstep; const char* cB = (const char*)g.Bt + (size_t)cur.pn * tstep;
;     S.a_ready(cur);
;     if constexpr (SP2) {
;         PG8_STAGE(PG8_SB(0, 0), cB, voffB); PG8_STAGE(PG8_SB(0, 1), cB + hstep, voffB); PG8_STAGE(PG8_SA(0, 0), cA, voffA); PG8_STAGE(PG8_SA(0, 1), cA + hstep, voffA);
;         if (wr == 1) PG8_BAR;
;         PG8_WAIT_V(2); PG8_BAR;
;         PG8_STAGE(PG8_SB(1, 0), cB + kstep, voffB); PG8_STAGE(PG8_SA(1, 0), cA + kstep, voffA); PG8_STAGE(PG8_SB(1, 1), cB + hstep + kstep, voffB);
;         PG8_WAIT_V(6); PG8_BAR;
.LBB0_237:
	s_add_u32 s31, s4, 0xd400000
	s_addc_u32 s34, s5, 0
	s_add_u32 s35, s4, 0x23400000
	s_addc_u32 s36, s5, 0
	s_lshl_b32 s7, s7, 5
	s_and_b32 s7, s7, 0x60
	s_add_i32 m0, s27, 0x18000
	v_lshl_add_u64 v[8:9], v[8:9], 0, s[94:95]
	s_lshl_b32 s37, s8, 6
	s_lshl_b32 s10, s8, 13
	s_lshl_b32 s11, s7, 7
	global_load_lds_dwordx4 v[8:9], off
	v_lshl_add_u64 v[6:7], v[6:7], 0, s[94:95]
	s_add_i32 m0, s27, 0x1a000
	s_add_i32 s38, s27, 0x8000
	s_add_i32 s39, s27, 0xa000
	global_load_lds_dwordx4 v[6:7], off
	v_lshl_add_u64 v[2:3], v[2:3], 0, s[94:95]
	s_mov_b32 m0, s38
	s_add_u32 s8, s16, 0x40080
	global_load_lds_dwordx4 v[2:3], off
	v_lshl_add_u64 v[2:3], v[4:5], 0, s[94:95]
	s_mov_b32 m0, s39
	s_addc_u32 s9, s17, 0
	global_load_lds_dwordx4 v[2:3], off
	s_add_i32 m0, s27, 0x1c000
	v_lshl_add_u64 v[2:3], s[8:9], 0, v[134:135]
	global_load_lds_dwordx4 v[2:3], off
	v_lshl_add_u64 v[2:3], s[8:9], 0, v[130:131]
	s_add_i32 m0, s27, 0x1e000
	v_and_b32_e32 v0, 15, v10
	global_load_lds_dwordx4 v[2:3], off
	s_waitcnt vmcnt(8)
	s_barrier
	v_lshrrev_b32_e32 v2, 1, v10
	v_and_b32_e32 v2, 24, v2
	v_lshlrev_b32_e32 v3, 1, v2
	v_lshlrev_b32_e32 v4, 2, v10
	v_or_b32_e32 v139, s37, v0
	v_lshl_or_b32 v3, v0, 6, v3
	v_and_b32_e32 v4, 32, v4
	v_or_b32_e32 v138, s7, v2
	v_mov_b32_e32 v2, 0x7ffa0000
	v_lshlrev_b32_e32 v0, 5, v0
	v_bitop3_b32 v5, v3, s10, v4 bitop3:0xde
	v_bitop3_b32 v147, v3, s11, v4 bitop3:0xde
	v_lshl_or_b32 v155, v138, 8, v2
	v_lshl_add_u64 v[2:3], s[4:5], 0, v[0:1]
	v_and_b32_e32 v0, 16, v10
	v_lshl_add_u64 v[2:3], v[2:3], 0, v[0:1]
	v_lshlrev_b32_e32 v0, 14, v15
	s_mov_b64 s[4:5], 0x19400000
	v_and_b32_e32 v0, 0xffff8000, v0
	v_lshl_add_u64 v[140:141], v[2:3], 0, s[4:5]
	v_lshl_add_u32 v0, v14, 11, v0
	v_and_b32_e32 v2, 1, v15
	v_lshl_or_b32 v0, v2, 6, v0
	v_lshl_add_u32 v142, v16, 1, v0
	v_lshlrev_b32_e32 v0, 14, v11
	v_and_b32_e32 v0, 0xffff8000, v0
	s_waitcnt vmcnt(6)
	v_lshl_add_u32 v0, v12, 11, v0
	v_and_b32_e32 v2, 1, v11
	s_cmpk_lt_u32 s6, 0x100
	v_lshl_or_b32 v0, v2, 6, v0
	v_readlane_b32 s4, v254, 60
	s_cselect_b64 s[6:7], -1, 0
	v_or_b32_e32 v148, 16, v139
	v_or_b32_e32 v149, 32, v139
	v_or_b32_e32 v150, 48, v139
	v_add_u32_e32 v151, 0x80, v139
	v_add_u32_e32 v152, 0x90, v139
	v_add_u32_e32 v153, 0xa0, v139
	v_add_u32_e32 v154, 0xb0, v139
	s_or_b32 s55, s37, 16
	s_or_b32 s97, s37, 32
	s_or_b32 s85, s37, 48
	v_mov_b32_e32 v143, v1
	v_lshl_add_u32 v144, v13, 1, v0
	v_mov_b32_e32 v145, v1
	s_mov_b32 s66, 0
	v_add_u32_e32 v156, 0, v5
	v_readlane_b32 s56, v254, 59
	s_mov_b32 s33, s4
	s_barrier
	v_readlane_b32 s5, v254, 61
	s_branch .LBB0_240

; #define PG8_STAGE(bufoff, gbase, voff) do { _Pragma("unroll") for (int _i = 0; _i < 2; ++_i) \
;         __builtin_amdgcn_global_load_lds((const unsigned*)((const char*)(gbase) + (voff)[_i]), (PG8_LAS unsigned*)(lds + (bufoff) + ldsw + _i * 8192), 16, 0, 0); } while (0)
; #define PG8_WAIT_V(n) asm volatile("s_waitcnt vmcnt(" #n ")" ::: "memory")
; #define PG8_BAR __builtin_amdgcn_s_barrier()
; template <class Epi, class Sched, bool ALIGN_EPI = false, bool SP2 = false>
; __device__ __forceinline__ void gemm_phase(PG8_LAS unsigned char* lds, const Gemm g, const Sched& S, const Epi& E) {
;     ...
;     const char* cA = (const char*)g.A + (size_t)cur.pm * tstep; const char* cB = (const char*)g.Bt + (size_t)cur.pn * tstep;
;     S.a_ready(cur);
;     if constexpr (SP2) {
;         PG8_STAGE(PG8_SB(0, 0), cB, voffB); PG8_STAGE(PG8_SB(0, 1), cB + hstep, voffB); PG8_STAGE(PG8_SA(0, 0), cA, voffA); PG8_STAGE(PG8_SA(0, 1), cA + hstep, voffA);
;         if (wr == 1) PG8_BAR;
;         PG8_WAIT_V(2); PG8_BAR;
;         PG8_STAGE(PG8_SB(1, 0), cB + kstep, voffB); PG8_STAGE(PG8_SA(1, 0), cA + kstep, voffA); PG8_STAGE(PG8_SB(1, 1), cB + hstep + kstep, voffB);
;         PG8_WAIT_V(6); PG8_BAR;
.LBB0_310:
	v_lshrrev_b32_e32 v12, 1, v10
	v_and_b32_e32 v12, 24, v12
	s_lshl_b32 s7, s7, 5
	v_and_b32_e32 v11, 15, v10
	v_lshlrev_b32_e32 v13, 1, v12
	v_lshlrev_b32_e32 v10, 2, v10
	s_and_b32 s10, s7, 0x60
	s_add_i32 m0, s21, 0x18000
	v_lshl_add_u64 v[8:9], v[8:9], 0, s[94:95]
	v_lshl_or_b32 v74, s8, 6, v11
	v_lshl_or_b32 v11, v11, 6, v13
	s_lshl_b32 s8, s8, 13
	v_and_b32_e32 v10, 32, v10
	s_lshl_b32 s7, s10, 7
	global_load_lds_dwordx4 v[8:9], off
	v_lshl_add_u64 v[6:7], v[6:7], 0, s[94:95]
	s_add_i32 m0, s21, 0x1a000
	s_add_i32 s27, s21, 0x8000
	s_add_i32 s28, s21, 0xa000
	v_bitop3_b32 v13, v11, s8, v10 bitop3:0xde
	global_load_lds_dwordx4 v[6:7], off
	v_lshl_add_u64 v[2:3], v[2:3], 0, s[94:95]
	s_mov_b32 m0, s27
	s_add_u32 s8, s16, 0x18080
	global_load_lds_dwordx4 v[2:3], off
	v_lshl_add_u64 v[2:3], v[4:5], 0, s[94:95]
	s_mov_b32 m0, s28
	s_addc_u32 s9, s17, 0
	s_add_i32 s29, s21, 0x1c000
	global_load_lds_dwordx4 v[2:3], off
	v_lshl_add_u64 v[2:3], s[8:9], 0, v[0:1]
	s_mov_b32 m0, s29
	s_add_i32 s30, s21, 0x1e000
	global_load_lds_dwordx4 v[2:3], off
	v_lshl_add_u64 v[2:3], s[8:9], 0, v[66:67]
	s_mov_b32 m0, s30
	s_mov_b64 s[8:9], 0x1f400000
	global_load_lds_dwordx4 v[2:3], off
	s_waitcnt vmcnt(8)
	s_barrier
	v_or_b32_e32 v2, s10, v12
	v_lshlrev_b32_e32 v2, 2, v2
	v_mov_b32_e32 v3, v1
	v_lshl_add_u64 v[2:3], s[4:5], 0, v[2:3]
	s_waitcnt vmcnt(6)
	s_cmpk_lt_u32 s6, 0x100
	v_lshl_add_u64 v[72:73], v[2:3], 0, s[8:9]
	v_readlane_b32 s8, v255, 27
	v_bitop3_b32 v75, v11, s7, v10 bitop3:0xde
	s_cselect_b64 s[6:7], -1, 0
	s_add_u32 s8, s4, s8
	v_readlane_b32 s4, v255, 28
	v_or_b32_e32 v76, 16, v74
	v_or_b32_e32 v77, 32, v74
	v_or_b32_e32 v78, 48, v74
	s_addc_u32 s9, s5, s4
	s_mov_b32 s31, 0
	v_add_u32_e32 v79, 0, v13
	v_readlane_b32 s33, v255, 26
	s_mov_b32 s34, s2
	s_mov_b64 s[10:11], s[14:15]
	s_barrier
	s_branch .LBB0_313

; #define PG8_STAGE(bufoff, gbase, voff) do { _Pragma("unroll") for (int _i = 0; _i < 2; ++_i) \
;         __builtin_amdgcn_global_load_lds((const unsigned*)((const char*)(gbase) + (voff)[_i]), (PG8_LAS unsigned*)(lds + (bufoff) + ldsw + _i * 8192), 16, 0, 0); } while (0)
; #define PG8_WAIT_V(n) asm volatile("s_waitcnt vmcnt(" #n ")" ::: "memory")
; #define PG8_BAR __builtin_amdgcn_s_barrier()
; template <class Epi, class Sched, bool ALIGN_EPI = false, bool SP2 = false>
; __device__ __forceinline__ void gemm_phase(PG8_LAS unsigned char* lds, const Gemm g, const Sched& S, const Epi& E) {
;     ...
;     const char* cA = (const char*)g.A + (size_t)cur.pm * tstep; const char* cB = (const char*)g.Bt + (size_t)cur.pn * tstep;
;     S.a_ready(cur);
;     if constexpr (SP2) {
;         PG8_STAGE(PG8_SB(0, 0), cB, voffB); PG8_STAGE(PG8_SB(0, 1), cB + hstep, voffB); PG8_STAGE(PG8_SA(0, 0), cA, voffA); PG8_STAGE(PG8_SA(0, 1), cA + hstep, voffA);
;         if (wr == 1) PG8_BAR;
;         PG8_WAIT_V(2); PG8_BAR;
;         PG8_STAGE(PG8_SB(1, 0), cB + kstep, voffB); PG8_STAGE(PG8_SA(1, 0), cA + kstep, voffA); PG8_STAGE(PG8_SB(1, 1), cB + hstep + kstep, voffB);
;         PG8_WAIT_V(6); PG8_BAR;
.LBB0_384:
	v_lshrrev_b32_e32 v10, 1, v0
	s_add_u32 s6, s4, 0x1f400000
	v_and_b32_e32 v140, 15, v0
	v_and_b32_e32 v11, 24, v10
	s_addc_u32 s7, s5, 0
	v_lshlrev_b32_e32 v12, 1, v11
	v_lshlrev_b32_e32 v13, 6, v140
	v_lshlrev_b32_e32 v0, 2, v0
	s_lshl_b32 s9, s9, 12
	s_add_i32 m0, s25, 0x18000
	v_lshl_add_u64 v[8:9], v[8:9], 0, s[94:95]
	s_lshl_b32 s29, s10, 6
	v_or_b32_e32 v14, v13, v12
	s_lshl_b32 s10, s10, 13
	v_and_b32_e32 v0, 32, v0
	s_and_b32 s9, s9, 0x3000
	global_load_lds_dwordx4 v[8:9], off
	v_lshl_add_u64 v[6:7], v[6:7], 0, s[94:95]
	s_add_i32 m0, s25, 0x1a000
	s_add_i32 s30, s25, 0x8000
	s_add_i32 s31, s25, 0xa000
	v_bitop3_b32 v12, v13, v0, v12 bitop3:0x36
	v_bitop3_b32 v0, v14, s10, v0 bitop3:0xde
	global_load_lds_dwordx4 v[6:7], off
	v_lshl_add_u64 v[2:3], v[2:3], 0, s[94:95]
	s_mov_b32 m0, s30
	s_add_u32 s10, s20, 0x18080
	global_load_lds_dwordx4 v[2:3], off
	v_lshl_add_u64 v[2:3], v[4:5], 0, s[94:95]
	s_mov_b32 m0, s31
	s_addc_u32 s11, s21, 0
	global_load_lds_dwordx4 v[2:3], off
	s_add_i32 m0, s25, 0x1c000
	v_lshl_add_u64 v[2:3], s[10:11], 0, v[134:135]
	global_load_lds_dwordx4 v[2:3], off
	v_lshl_add_u64 v[2:3], s[10:11], 0, v[130:131]
	s_add_i32 m0, s25, 0x1e000
	s_cmpk_lt_u32 s8, 0x100
	global_load_lds_dwordx4 v[2:3], off
	s_waitcnt vmcnt(8)
	s_barrier
	s_waitcnt vmcnt(6)
	v_lshlrev_b32_e32 v2, 5, v11
	v_mov_b32_e32 v3, 0xe00
	v_readlane_b32 s10, v255, 27
	v_or_b32_e32 v141, s9, v12
	v_add_u32_e32 v142, 0, v0
	s_cselect_b64 s[8:9], -1, 0
	v_and_b32_e32 v0, 8, v10
	v_bitop3_b32 v143, s24, v3, v2 bitop3:0xc8
	s_add_u32 s10, s4, s10
	v_readlane_b32 s4, v255, 28
	v_or_b32_e32 v144, 0x1000, v143
	s_addc_u32 s11, s5, s4
	s_mov_b32 s34, 0
	v_lshlrev_b32_e32 v138, 1, v0
	v_readlane_b32 s35, v255, 26
	s_mov_b32 s33, s2
	s_mov_b64 s[12:13], s[18:19]
	s_barrier
	s_branch .LBB0_387

; #define PG8_STAGE(bufoff, gbase, voff) do { _Pragma("unroll") for (int _i = 0; _i < 2; ++_i) \
;         __builtin_amdgcn_global_load_lds((const unsigned*)((const char*)(gbase) + (voff)[_i]), (PG8_LAS unsigned*)(lds + (bufoff) + ldsw + _i * 8192), 16, 0, 0); } while (0)
; #define PG8_WAIT_V(n) asm volatile("s_waitcnt vmcnt(" #n ")" ::: "memory")
; #define PG8_BAR __builtin_amdgcn_s_barrier()
; template <class Epi, class Sched, bool ALIGN_EPI = false, bool SP2 = false>
; __device__ __forceinline__ void gemm_phase(PG8_LAS unsigned char* lds, const Gemm g, const Sched& S, const Epi& E) {
;     ...
;     const char* cA = (const char*)g.A + (size_t)cur.pm * tstep; const char* cB = (const char*)g.Bt + (size_t)cur.pn * tstep;
;     S.a_ready(cur);
;     if constexpr (SP2) {
;         PG8_STAGE(PG8_SB(0, 0), cB, voffB); PG8_STAGE(PG8_SB(0, 1), cB + hstep, voffB); PG8_STAGE(PG8_SA(0, 0), cA, voffA); PG8_STAGE(PG8_SA(0, 1), cA + hstep, voffA);
;         if (wr == 1) PG8_BAR;
;         PG8_WAIT_V(2); PG8_BAR;
;         PG8_STAGE(PG8_SB(1, 0), cB + kstep, voffB); PG8_STAGE(PG8_SA(1, 0), cA + kstep, voffA); PG8_STAGE(PG8_SB(1, 1), cB + hstep + kstep, voffB);
;         PG8_WAIT_V(6); PG8_BAR;
.LBB0_537:
	s_lshl_b64 s[6:7], s[60:61], 11
	v_readlane_b32 s48, v254, 29
	v_readlane_b32 s58, v254, 39
	v_readlane_b32 s59, v254, 40
	s_add_u32 s6, s58, s6
	v_lshrrev_b32_e32 v17, 1, v15
	s_addc_u32 s7, s59, s7
	v_and_b32_e32 v17, 24, v17
	s_add_u32 s8, s4, 0xd400000
	v_and_b32_e32 v16, 15, v15
	v_lshlrev_b32_e32 v18, 1, v17
	v_lshlrev_b32_e32 v15, 2, v15
	s_addc_u32 s9, s5, 0
	v_lshl_or_b32 v211, s12, 6, v16
	v_lshl_or_b32 v16, v16, 6, v18
	s_lshl_b32 s4, s12, 13
	v_and_b32_e32 v15, 32, v15
	v_bitop3_b32 v18, v16, s4, v15 bitop3:0xde
	s_lshl_b32 s4, s11, 5
	s_and_b32 s12, s4, 0x60
	s_add_i32 m0, s31, 0x18000
	v_lshl_add_u64 v[8:9], v[8:9], 0, s[94:95]
	s_lshl_b32 s4, s12, 7
	global_load_lds_dwordx4 v[8:9], off
	v_lshl_add_u64 v[6:7], v[6:7], 0, s[94:95]
	s_add_i32 m0, s31, 0x1a000
	s_add_i32 s37, s31, 0x8000
	s_add_i32 s38, s31, 0xa000
	v_bitop3_b32 v244, v16, s4, v15 bitop3:0xde
	global_load_lds_dwordx4 v[6:7], off
	v_lshl_add_u64 v[2:3], v[2:3], 0, s[94:95]
	s_mov_b32 m0, s37
	s_add_u32 s4, s16, 0x20080
	global_load_lds_dwordx4 v[2:3], off
	v_lshl_add_u64 v[2:3], v[4:5], 0, s[94:95]
	s_mov_b32 m0, s38
	s_addc_u32 s5, s17, 0
	global_load_lds_dwordx4 v[2:3], off
	s_add_i32 m0, s31, 0x1c000
	v_lshl_add_u64 v[2:3], s[4:5], 0, v[206:207]
	global_load_lds_dwordx4 v[2:3], off
	v_lshl_add_u64 v[2:3], s[4:5], 0, v[202:203]
	s_add_i32 m0, s31, 0x1e000
	v_readlane_b32 s49, v254, 30
	global_load_lds_dwordx4 v[2:3], off
	s_waitcnt vmcnt(8)
	s_barrier
	v_lshlrev_b32_e32 v2, 13, v13
	v_and_b32_e32 v2, 0xffffc000, v2
	v_lshl_add_u32 v2, v12, 10, v2
	v_and_b32_e32 v3, 1, v13
	v_lshl_or_b32 v2, v3, 6, v2
	v_lshl_add_u32 v220, v14, 1, v2
	v_lshlrev_b32_e32 v2, 13, v0
	v_and_b32_e32 v2, 0xffffc000, v2
	s_waitcnt vmcnt(6)
	v_lshl_add_u32 v2, v10, 10, v2
	v_and_b32_e32 v0, 1, v0
	v_readlane_b32 s54, v254, 35
	v_readlane_b32 s62, v254, 43
	s_cmpk_lt_u32 s10, 0x100
	v_lshl_or_b32 v0, v0, 6, v2
	v_readlane_b32 s4, v255, 3
	v_readlane_b32 s51, v254, 32
	s_cselect_b64 s[10:11], -1, 0
	v_or_b32_e32 v210, s12, v17
	v_mov_b32_e32 v221, v1
	v_lshl_add_u32 v222, v11, 1, v0
	v_mov_b32_e32 v223, v1
	s_mov_b32 s39, 0
	v_add_u32_e32 v245, 0, v18
	v_readlane_b32 s46, v255, 2
	s_mov_b32 s33, s4
	s_mov_b32 s48, s13
	s_mov_b64 s[58:59], s[18:19]
	s_mov_b32 s49, 0x30000
	s_mov_b32 s54, s15
	s_mov_b32 s62, s20
	v_readlane_b32 s50, v254, 31
	v_readlane_b32 s52, v254, 33
	v_readlane_b32 s53, v254, 34
	v_readlane_b32 s55, v254, 36
	v_readlane_b32 s56, v254, 37
	v_readlane_b32 s57, v254, 38
	v_readlane_b32 s60, v254, 41
	v_readlane_b32 s61, v254, 42
	v_readlane_b32 s63, v254, 44
	s_barrier
	v_readlane_b32 s5, v255, 4
	v_readlane_b32 s51, v255, 32
	s_branch .LBB0_540

; #define PG8_STAGE(bufoff, gbase, voff) do { _Pragma("unroll") for (int _i = 0; _i < 2; ++_i) \
;         __builtin_amdgcn_global_load_lds((const unsigned*)((const char*)(gbase) + (voff)[_i]), (PG8_LAS unsigned*)(lds + (bufoff) + ldsw + _i * 8192), 16, 0, 0); } while (0)
; #define PG8_WAIT_V(n) asm volatile("s_waitcnt vmcnt(" #n ")" ::: "memory")
; #define PG8_BAR __builtin_amdgcn_s_barrier()
; template <class Epi, class Sched, bool ALIGN_EPI = false, bool SP2 = false>
; __device__ __forceinline__ void gemm_phase(PG8_LAS unsigned char* lds, const Gemm g, const Sched& S, const Epi& E) {
;     ...
;     const char* cA = (const char*)g.A + (size_t)cur.pm * tstep; const char* cB = (const char*)g.Bt + (size_t)cur.pn * tstep;
;     S.a_ready(cur);
;     if constexpr (SP2) {
;         PG8_STAGE(PG8_SB(0, 0), cB, voffB); PG8_STAGE(PG8_SB(0, 1), cB + hstep, voffB); PG8_STAGE(PG8_SA(0, 0), cA, voffA); PG8_STAGE(PG8_SA(0, 1), cA + hstep, voffA);
;         if (wr == 1) PG8_BAR;
;         PG8_WAIT_V(2); PG8_BAR;
;         PG8_STAGE(PG8_SB(1, 0), cB + kstep, voffB); PG8_STAGE(PG8_SA(1, 0), cA + kstep, voffA); PG8_STAGE(PG8_SB(1, 1), cB + hstep + kstep, voffB);
;         PG8_WAIT_V(6); PG8_BAR;
.LBB0_557:
	s_add_u32 s35, s4, 0x23400000
	v_lshrrev_b32_e32 v17, 1, v15
	s_addc_u32 s36, s5, 0
	v_and_b32_e32 v17, 24, v17
	s_add_u32 s6, s4, 0x11400000
	v_and_b32_e32 v16, 15, v15
	v_lshlrev_b32_e32 v18, 1, v17
	v_lshlrev_b32_e32 v15, 2, v15
	s_addc_u32 s7, s5, 0
	v_lshl_or_b32 v170, s10, 6, v16
	v_lshl_or_b32 v16, v16, 6, v18
	s_lshl_b32 s4, s10, 13
	v_and_b32_e32 v15, 32, v15
	v_bitop3_b32 v18, v16, s4, v15 bitop3:0xde
	s_lshl_b32 s4, s9, 5
	s_and_b32 s10, s4, 0x60
	s_add_i32 m0, s29, 0x18000
	v_lshl_add_u64 v[8:9], v[8:9], 0, s[94:95]
	s_lshl_b32 s4, s10, 7
	global_load_lds_dwordx4 v[8:9], off
	v_lshl_add_u64 v[6:7], v[6:7], 0, s[94:95]
	s_add_i32 m0, s29, 0x1a000
	s_add_i32 s33, s29, 0x8000
	s_add_i32 s37, s29, 0xa000
	v_bitop3_b32 v171, v16, s4, v15 bitop3:0xde
	global_load_lds_dwordx4 v[6:7], off
	v_lshl_add_u64 v[2:3], v[2:3], 0, s[94:95]
	s_mov_b32 m0, s33
	s_add_u32 s4, s16, 0x20080
	global_load_lds_dwordx4 v[2:3], off
	v_lshl_add_u64 v[2:3], v[4:5], 0, s[94:95]
	s_mov_b32 m0, s37
	s_addc_u32 s5, s17, 0
	global_load_lds_dwordx4 v[2:3], off
	s_add_i32 m0, s29, 0x1c000
	v_lshl_add_u64 v[2:3], s[4:5], 0, v[154:155]
	global_load_lds_dwordx4 v[2:3], off
	v_lshl_add_u64 v[2:3], s[4:5], 0, v[150:151]
	s_add_i32 m0, s29, 0x1e000
	v_and_b32_e32 v4, 1, v13
	global_load_lds_dwordx4 v[2:3], off
	s_waitcnt vmcnt(8)
	s_barrier
	v_lshlrev_b32_e32 v3, 13, v13
	v_and_b32_e32 v3, 0xffffc000, v3
	v_lshl_add_u32 v3, v12, 10, v3
	v_lshl_or_b32 v3, v4, 6, v3
	v_lshl_add_u32 v158, v14, 1, v3
	v_lshlrev_b32_e32 v3, 13, v0
	v_and_b32_e32 v3, 0xffffc000, v3
	s_waitcnt vmcnt(6)
	v_lshl_add_u32 v3, v10, 10, v3
	v_and_b32_e32 v0, 1, v0
	s_cmpk_lt_u32 s8, 0x100
	v_or_b32_e32 v2, s10, v17
	v_lshl_or_b32 v0, v0, 6, v3
	v_readlane_b32 s4, v255, 18
	s_cselect_b64 s[8:9], -1, 0
	v_mov_b32_e32 v159, v1
	v_lshl_add_u32 v160, v11, 1, v0
	v_mov_b32_e32 v161, v1
	s_mov_b32 s38, 0
	v_add_u32_e32 v172, 0, v18
	v_lshlrev_b32_e32 v0, 1, v2
	v_readlane_b32 s39, v255, 9
	s_mov_b32 s46, s4
	s_barrier
	v_readlane_b32 s5, v255, 19
	s_branch .LBB0_560

; #define PG8_STAGE(bufoff, gbase, voff) do { _Pragma("unroll") for (int _i = 0; _i < 2; ++_i) \
;         __builtin_amdgcn_global_load_lds((const unsigned*)((const char*)(gbase) + (voff)[_i]), (PG8_LAS unsigned*)(lds + (bufoff) + ldsw + _i * 8192), 16, 0, 0); } while (0)
; #define PG8_WAIT_V(n) asm volatile("s_waitcnt vmcnt(" #n ")" ::: "memory")
; #define PG8_BAR __builtin_amdgcn_s_barrier()
; template <class Epi, class Sched, bool ALIGN_EPI = false, bool SP2 = false>
; __device__ __forceinline__ void gemm_phase(PG8_LAS unsigned char* lds, const Gemm g, const Sched& S, const Epi& E) {
;     ...
;     const char* cA = (const char*)g.A + (size_t)cur.pm * tstep; const char* cB = (const char*)g.Bt + (size_t)cur.pn * tstep;
;     S.a_ready(cur);
;     if constexpr (SP2) {
;         PG8_STAGE(PG8_SB(0, 0), cB, voffB); PG8_STAGE(PG8_SB(0, 1), cB + hstep, voffB); PG8_STAGE(PG8_SA(0, 0), cA, voffA); PG8_STAGE(PG8_SA(0, 1), cA + hstep, voffA);
;         if (wr == 1) PG8_BAR;
;         PG8_WAIT_V(2); PG8_BAR;
;         PG8_STAGE(PG8_SB(1, 0), cB + kstep, voffB); PG8_STAGE(PG8_SA(1, 0), cA + kstep, voffA); PG8_STAGE(PG8_SB(1, 1), cB + hstep + kstep, voffB);
;         PG8_WAIT_V(6); PG8_BAR;
.LBB0_622:
	s_add_u32 s6, s4, 0x2b400000
	v_lshrrev_b32_e32 v17, 1, v15
	s_addc_u32 s7, s5, 0
	v_and_b32_e32 v17, 24, v17
	s_add_u32 s8, s4, 0x11400000
	v_and_b32_e32 v16, 15, v15
	v_lshlrev_b32_e32 v18, 1, v17
	v_lshlrev_b32_e32 v15, 2, v15
	s_addc_u32 s9, s5, 0
	v_lshl_or_b32 v203, s12, 6, v16
	v_lshl_or_b32 v16, v16, 6, v18
	s_lshl_b32 s4, s12, 13
	v_and_b32_e32 v15, 32, v15
	v_bitop3_b32 v18, v16, s4, v15 bitop3:0xde
	s_lshl_b32 s4, s11, 5
	s_and_b32 s12, s4, 0x60
	s_add_i32 m0, s31, 0x18000
	v_lshl_add_u64 v[8:9], v[8:9], 0, s[94:95]
	s_lshl_b32 s4, s12, 7
	global_load_lds_dwordx4 v[8:9], off
	v_lshl_add_u64 v[6:7], v[6:7], 0, s[94:95]
	s_add_i32 m0, s31, 0x1a000
	s_add_i32 s37, s31, 0x8000
	s_add_i32 s38, s31, 0xa000
	v_bitop3_b32 v205, v16, s4, v15 bitop3:0xde
	global_load_lds_dwordx4 v[6:7], off
	v_lshl_add_u64 v[2:3], v[2:3], 0, s[94:95]
	s_mov_b32 m0, s37
	s_add_u32 s4, s16, 0x20080
	global_load_lds_dwordx4 v[2:3], off
	v_lshl_add_u64 v[2:3], v[4:5], 0, s[94:95]
	s_mov_b32 m0, s38
	s_addc_u32 s5, s17, 0
	global_load_lds_dwordx4 v[2:3], off
	s_add_i32 m0, s31, 0x1c000
	v_lshl_add_u64 v[2:3], s[4:5], 0, v[198:199]
	global_load_lds_dwordx4 v[2:3], off
	v_lshl_add_u64 v[2:3], s[4:5], 0, v[194:195]
	s_add_i32 m0, s31, 0x1e000
	s_cmpk_lt_u32 s10, 0x100
	global_load_lds_dwordx4 v[2:3], off
	s_waitcnt vmcnt(8)
	s_barrier
	v_lshlrev_b32_e32 v2, 13, v13
	v_and_b32_e32 v2, 0xffffc000, v2
	v_lshl_add_u32 v2, v12, 10, v2
	v_and_b32_e32 v3, 1, v13
	v_lshl_or_b32 v2, v3, 6, v2
	v_lshl_add_u32 v206, v14, 1, v2
	v_lshlrev_b32_e32 v2, 13, v0
	v_and_b32_e32 v2, 0xffffc000, v2
	s_waitcnt vmcnt(6)
	v_lshl_add_u32 v2, v10, 10, v2
	v_and_b32_e32 v0, 1, v0
	v_or_b32_e32 v202, s12, v17
	v_lshl_or_b32 v0, v0, 6, v2
	v_readlane_b32 s4, v255, 18
	s_cselect_b64 s[10:11], -1, 0
	v_or_b32_e32 v204, 0x80, v202
	v_mov_b32_e32 v207, v1
	v_lshl_add_u32 v208, v11, 1, v0
	v_mov_b32_e32 v209, v1
	s_mov_b32 s39, 0
	v_add_u32_e32 v226, 0, v18
	v_readlane_b32 s33, v255, 9
	s_mov_b32 s46, s4
	s_barrier
	v_readlane_b32 s5, v255, 19
	s_branch .LBB0_625

; #define PG8_STAGE(bufoff, gbase, voff) do { _Pragma("unroll") for (int _i = 0; _i < 2; ++_i) \
;         __builtin_amdgcn_global_load_lds((const unsigned*)((const char*)(gbase) + (voff)[_i]), (PG8_LAS unsigned*)(lds + (bufoff) + ldsw + _i * 8192), 16, 0, 0); } while (0)
; #define PG8_WAIT_V(n) asm volatile("s_waitcnt vmcnt(" #n ")" ::: "memory")
; #define PG8_BAR __builtin_amdgcn_s_barrier()
; template <class Epi, class Sched, bool ALIGN_EPI = false, bool SP2 = false>
; __device__ __forceinline__ void gemm_phase(PG8_LAS unsigned char* lds, const Gemm g, const Sched& S, const Epi& E) {
;     ...
;     const char* cA = (const char*)g.A + (size_t)cur.pm * tstep; const char* cB = (const char*)g.Bt + (size_t)cur.pn * tstep;
;     S.a_ready(cur);
;     if constexpr (SP2) {
;         PG8_STAGE(PG8_SB(0, 0), cB, voffB); PG8_STAGE(PG8_SB(0, 1), cB + hstep, voffB); PG8_STAGE(PG8_SA(0, 0), cA, voffA); PG8_STAGE(PG8_SA(0, 1), cA + hstep, voffA);
;         if (wr == 1) PG8_BAR;
;         PG8_WAIT_V(2); PG8_BAR;
;         PG8_STAGE(PG8_SB(1, 0), cB + kstep, voffB); PG8_STAGE(PG8_SA(1, 0), cA + kstep, voffA); PG8_STAGE(PG8_SB(1, 1), cB + hstep + kstep, voffB);
;         PG8_WAIT_V(6); PG8_BAR;
.LBB0_687:
	v_lshrrev_b32_e32 v17, 1, v15
	v_and_b32_e32 v17, 24, v17
	s_add_u32 s6, s4, 0x33400000
	v_and_b32_e32 v16, 15, v15
	v_lshlrev_b32_e32 v18, 1, v17
	v_lshlrev_b32_e32 v15, 2, v15
	s_addc_u32 s7, s5, 0
	v_lshl_or_b32 v230, s10, 6, v16
	v_lshl_or_b32 v16, v16, 6, v18
	s_lshl_b32 s4, s10, 13
	v_and_b32_e32 v15, 32, v15
	v_bitop3_b32 v18, v16, s4, v15 bitop3:0xde
	s_lshl_b32 s4, s9, 5
	s_and_b32 s10, s4, 0x60
	s_add_i32 m0, s29, 0x18000
	v_lshl_add_u64 v[8:9], v[8:9], 0, s[94:95]
	s_lshl_b32 s4, s10, 7
	global_load_lds_dwordx4 v[8:9], off
	v_lshl_add_u64 v[6:7], v[6:7], 0, s[94:95]
	s_add_i32 m0, s29, 0x1a000
	s_add_i32 s33, s29, 0x8000
	s_add_i32 s35, s29, 0xa000
	v_bitop3_b32 v231, v16, s4, v15 bitop3:0xde
	global_load_lds_dwordx4 v[6:7], off
	v_lshl_add_u64 v[2:3], v[2:3], 0, s[94:95]
	s_mov_b32 m0, s33
	s_add_u32 s4, s16, 0x40080
	global_load_lds_dwordx4 v[2:3], off
	v_lshl_add_u64 v[2:3], v[4:5], 0, s[94:95]
	s_mov_b32 m0, s35
	s_addc_u32 s5, s17, 0
	global_load_lds_dwordx4 v[2:3], off
	s_add_i32 m0, s29, 0x1c000
	v_lshl_add_u64 v[2:3], s[4:5], 0, v[198:199]
	global_load_lds_dwordx4 v[2:3], off
	v_lshl_add_u64 v[2:3], s[4:5], 0, v[194:195]
	s_add_i32 m0, s29, 0x1e000
	v_and_b32_e32 v4, 1, v13
	global_load_lds_dwordx4 v[2:3], off
	s_waitcnt vmcnt(8)
	s_barrier
	v_lshlrev_b32_e32 v3, 14, v13
	v_and_b32_e32 v3, 0xffff8000, v3
	v_lshl_add_u32 v3, v12, 11, v3
	v_lshl_or_b32 v3, v4, 6, v3
	v_lshl_add_u32 v202, v14, 1, v3
	v_lshlrev_b32_e32 v3, 14, v0
	v_and_b32_e32 v3, 0xffff8000, v3
	s_waitcnt vmcnt(6)
	v_lshl_add_u32 v3, v10, 11, v3
	v_and_b32_e32 v0, 1, v0
	s_cmpk_lt_u32 s8, 0x100
	v_or_b32_e32 v2, s10, v17
	v_lshl_or_b32 v0, v0, 6, v3
	v_readlane_b32 s4, v255, 18
	s_cselect_b64 s[8:9], -1, 0
	v_mov_b32_e32 v203, v1
	v_lshl_add_u32 v204, v11, 1, v0
	v_mov_b32_e32 v205, v1
	s_mov_b32 s36, 0
	v_add_u32_e32 v232, 0, v18
	v_lshlrev_b32_e32 v0, 1, v2
	v_readlane_b32 s37, v255, 9
	s_mov_b32 s38, s4
	s_barrier
	v_readlane_b32 s5, v255, 19
	s_branch .LBB0_690

; #define PG8_STAGE(bufoff, gbase, voff) do { _Pragma("unroll") for (int _i = 0; _i < 2; ++_i) \
;         __builtin_amdgcn_global_load_lds((const unsigned*)((const char*)(gbase) + (voff)[_i]), (PG8_LAS unsigned*)(lds + (bufoff) + ldsw + _i * 8192), 16, 0, 0); } while (0)
; #define PG8_WAIT_V(n) asm volatile("s_waitcnt vmcnt(" #n ")" ::: "memory")
; #define PG8_BAR __builtin_amdgcn_s_barrier()
; template <class Epi, class Sched, bool ALIGN_EPI = false, bool SP2 = false>
; __device__ __forceinline__ void gemm_phase(PG8_LAS unsigned char* lds, const Gemm g, const Sched& S, const Epi& E) {
;     ...
;     const char* cA = (const char*)g.A + (size_t)cur.pm * tstep; const char* cB = (const char*)g.Bt + (size_t)cur.pn * tstep;
;     S.a_ready(cur);
;     if constexpr (SP2) {
;         PG8_STAGE(PG8_SB(0, 0), cB, voffB); PG8_STAGE(PG8_SB(0, 1), cB + hstep, voffB); PG8_STAGE(PG8_SA(0, 0), cA, voffA); PG8_STAGE(PG8_SA(0, 1), cA + hstep, voffA);
;         if (wr == 1) PG8_BAR;
;         PG8_WAIT_V(2); PG8_BAR;
;         PG8_STAGE(PG8_SB(1, 0), cB + kstep, voffB); PG8_STAGE(PG8_SA(1, 0), cA + kstep, voffA); PG8_STAGE(PG8_SB(1, 1), cB + hstep + kstep, voffB);
;         PG8_WAIT_V(6); PG8_BAR;
.LBB0_806:
	v_lshrrev_b32_e32 v17, 1, v15
	v_and_b32_e32 v17, 24, v17
	s_add_u32 s6, s4, 0xd400000
	v_and_b32_e32 v16, 15, v15
	v_lshlrev_b32_e32 v18, 1, v17
	v_lshlrev_b32_e32 v15, 2, v15
	s_addc_u32 s7, s5, 0
	v_lshl_or_b32 v144, s10, 6, v16
	v_lshl_or_b32 v16, v16, 6, v18
	s_lshl_b32 s4, s10, 13
	v_and_b32_e32 v15, 32, v15
	v_bitop3_b32 v18, v16, s4, v15 bitop3:0xde
	s_lshl_b32 s4, s9, 5
	s_and_b32 s10, s4, 0x60
	s_add_i32 m0, s29, 0x18000
	v_lshl_add_u64 v[8:9], v[8:9], 0, s[94:95]
	s_lshl_b32 s4, s10, 7
	global_load_lds_dwordx4 v[8:9], off
	v_lshl_add_u64 v[6:7], v[6:7], 0, s[94:95]
	s_add_i32 m0, s29, 0x1a000
	s_add_i32 s34, s29, 0x8000
	s_add_i32 s35, s29, 0xa000
	v_bitop3_b32 v145, v16, s4, v15 bitop3:0xde
	global_load_lds_dwordx4 v[6:7], off
	v_lshl_add_u64 v[2:3], v[2:3], 0, s[94:95]
	s_mov_b32 m0, s34
	s_add_u32 s4, s16, 0x40080
	global_load_lds_dwordx4 v[2:3], off
	v_lshl_add_u64 v[2:3], v[4:5], 0, s[94:95]
	s_mov_b32 m0, s35
	s_addc_u32 s5, s17, 0
	global_load_lds_dwordx4 v[2:3], off
	s_add_i32 m0, s29, 0x1c000
	v_lshl_add_u64 v[2:3], s[4:5], 0, v[134:135]
	global_load_lds_dwordx4 v[2:3], off
	v_lshl_add_u64 v[2:3], s[4:5], 0, v[130:131]
	s_add_i32 m0, s29, 0x1e000
	v_and_b32_e32 v4, 1, v13
	global_load_lds_dwordx4 v[2:3], off
	s_waitcnt vmcnt(8)
	s_barrier
	v_lshlrev_b32_e32 v3, 14, v13
	v_and_b32_e32 v3, 0xffff8000, v3
	v_lshl_add_u32 v3, v12, 11, v3
	v_lshl_or_b32 v3, v4, 6, v3
	v_lshl_add_u32 v138, v14, 1, v3
	v_lshlrev_b32_e32 v3, 14, v0
	v_and_b32_e32 v3, 0xffff8000, v3
	s_waitcnt vmcnt(6)
	v_lshl_add_u32 v3, v10, 11, v3
	v_and_b32_e32 v0, 1, v0
	s_cmpk_lt_u32 s8, 0x100
	v_or_b32_e32 v2, s10, v17
	v_lshl_or_b32 v0, v0, 6, v3
	v_readlane_b32 s4, v254, 60
	s_cselect_b64 s[8:9], -1, 0
	v_mov_b32_e32 v139, v1
	v_lshl_add_u32 v140, v11, 1, v0
	v_mov_b32_e32 v141, v1
	s_mov_b32 s36, 0
	v_add_u32_e32 v146, 0, v18
	v_lshlrev_b32_e32 v0, 1, v2
	v_readlane_b32 s37, v254, 59
	s_mov_b32 s38, s4
	s_barrier
	v_readlane_b32 s5, v254, 61
	s_branch .LBB0_809

; #define PG8_STAGE(bufoff, gbase, voff) do { _Pragma("unroll") for (int _i = 0; _i < 2; ++_i) \
;         __builtin_amdgcn_global_load_lds((const unsigned*)((const char*)(gbase) + (voff)[_i]), (PG8_LAS unsigned*)(lds + (bufoff) + ldsw + _i * 8192), 16, 0, 0); } while (0)
; #define PG8_WAIT_V(n) asm volatile("s_waitcnt vmcnt(" #n ")" ::: "memory")
; #define PG8_BAR __builtin_amdgcn_s_barrier()
; template <class Epi, class Sched, bool ALIGN_EPI = false, bool SP2 = false>
; __device__ __forceinline__ void gemm_phase(PG8_LAS unsigned char* lds, const Gemm g, const Sched& S, const Epi& E) {
;     ...
;     const char* cA = (const char*)g.A + (size_t)cur.pm * tstep; const char* cB = (const char*)g.Bt + (size_t)cur.pn * tstep;
;     S.a_ready(cur);
;     if constexpr (SP2) {
;         PG8_STAGE(PG8_SB(0, 0), cB, voffB); PG8_STAGE(PG8_SB(0, 1), cB + hstep, voffB); PG8_STAGE(PG8_SA(0, 0), cA, voffA); PG8_STAGE(PG8_SA(0, 1), cA + hstep, voffA);
;         if (wr == 1) PG8_BAR;
;         PG8_WAIT_V(2); PG8_BAR;
;         PG8_STAGE(PG8_SB(1, 0), cB + kstep, voffB); PG8_STAGE(PG8_SA(1, 0), cA + kstep, voffA); PG8_STAGE(PG8_SB(1, 1), cB + hstep + kstep, voffB);
;         PG8_WAIT_V(6); PG8_BAR;
.LBB0_871:
	v_lshrrev_b32_e32 v17, 1, v15
	v_and_b32_e32 v17, 24, v17
	s_add_u32 s6, s4, 0x33400000
	v_and_b32_e32 v16, 15, v15
	v_lshlrev_b32_e32 v18, 1, v17
	v_lshlrev_b32_e32 v15, 2, v15
	s_addc_u32 s7, s5, 0
	v_lshl_or_b32 v230, s10, 6, v16
	v_lshl_or_b32 v16, v16, 6, v18
	s_lshl_b32 s4, s10, 13
	v_and_b32_e32 v15, 32, v15
	v_bitop3_b32 v18, v16, s4, v15 bitop3:0xde
	s_lshl_b32 s4, s9, 5
	s_and_b32 s10, s4, 0x60
	s_add_i32 m0, s29, 0x18000
	v_lshl_add_u64 v[8:9], v[8:9], 0, s[94:95]
	s_lshl_b32 s4, s10, 7
	global_load_lds_dwordx4 v[8:9], off
	v_lshl_add_u64 v[6:7], v[6:7], 0, s[94:95]
	s_add_i32 m0, s29, 0x1a000
	s_add_i32 s33, s29, 0x8000
	s_add_i32 s35, s29, 0xa000
	v_bitop3_b32 v231, v16, s4, v15 bitop3:0xde
	global_load_lds_dwordx4 v[6:7], off
	v_lshl_add_u64 v[2:3], v[2:3], 0, s[94:95]
	s_mov_b32 m0, s33
	s_add_u32 s4, s16, 0x100080
	global_load_lds_dwordx4 v[2:3], off
	v_lshl_add_u64 v[2:3], v[4:5], 0, s[94:95]
	s_mov_b32 m0, s35
	s_addc_u32 s5, s17, 0
	global_load_lds_dwordx4 v[2:3], off
	s_add_i32 m0, s29, 0x1c000
	v_lshl_add_u64 v[2:3], s[4:5], 0, v[198:199]
	global_load_lds_dwordx4 v[2:3], off
	v_lshl_add_u64 v[2:3], s[4:5], 0, v[194:195]
	s_add_i32 m0, s29, 0x1e000
	v_and_b32_e32 v4, 1, v13
	global_load_lds_dwordx4 v[2:3], off
	s_waitcnt vmcnt(8)
	s_barrier
	v_lshlrev_b32_e32 v3, 16, v13
	v_and_b32_e32 v3, 0xfffe0000, v3
	v_lshl_add_u32 v3, v12, 13, v3
	v_lshl_or_b32 v3, v4, 6, v3
	v_lshl_add_u32 v202, v14, 1, v3
	v_lshlrev_b32_e32 v3, 16, v0
	v_and_b32_e32 v3, 0xfffe0000, v3
	s_waitcnt vmcnt(6)
	v_lshl_add_u32 v3, v10, 13, v3
	v_and_b32_e32 v0, 1, v0
	s_cmpk_lt_u32 s8, 0x100
	v_or_b32_e32 v2, s10, v17
	v_lshl_or_b32 v0, v0, 6, v3
	v_readlane_b32 s4, v255, 18
	s_cselect_b64 s[8:9], -1, 0
	v_mov_b32_e32 v203, v1
	v_lshl_add_u32 v204, v11, 1, v0
	v_mov_b32_e32 v205, v1
	s_mov_b32 s36, 0
	v_add_u32_e32 v232, 0, v18
	v_lshlrev_b32_e32 v0, 1, v2
	v_readlane_b32 s37, v255, 9
	s_mov_b32 s38, s4
	s_barrier
	v_readlane_b32 s5, v255, 19
	s_branch .LBB0_874
